# compact hand-written epilogue for the u_a in-projection tiles (raw*nrm -> bf16 -> group-major layout), replacing the branchy compiler path that cost ~50k cycles per tile
# baseline (speedup 1.0000x reference)
.LBB0_123:
	s_cmp_eq_u32 s17, 0
	s_cbranch_scc0 .Lfe_chk
	s_cmp_lt_u32 s35, 4
	s_cbranch_scc1 .Lfe_ua
	s_branch .Lfe_slow
.Lfe_chk:
	s_cmp_eq_u32 s17, 2
	s_cbranch_scc0 .Lfe_fast
	s_cmp_lt_u32 s35, 12
	s_cbranch_scc1 .Lfe_fast

.Lfe_ua:
	s_lshl_b32 s19, s42, 8
	s_add_i32 s19, s19, s71
	v_or_b32_e32 v162, s19, v147
	v_lshl_or_b32 v130, s35, 8, v174
	ds_read_b32 v176, v172
	ds_read_b32 v178, v172 offset:64
	ds_read_b32 v180, v172 offset:128
	ds_read_b32 v182, v172 offset:192
	ds_read_b32 v184, v172 offset:512
	ds_read_b32 v186, v172 offset:576
	ds_read_b32 v188, v172 offset:640
	ds_read_b32 v190, v172 offset:704
	v_lshrrev_b32_e32 v131, 4, v130
	v_and_b32_e32 v132, 15, v130
	v_lshlrev_b32_e32 v165, 18, v131
	v_lshl_add_u32 v165, v162, 5, v165
	v_lshl_add_u32 v165, v132, 1, v165
	v_readlane_b32 s44, v251, 26
	v_readlane_b32 s45, v251, 27
	s_waitcnt lgkmcnt(0)
	v_pk_mul_f32 v[126:127], v[126:127], v[176:177] op_sel_hi:[1,0]
	v_pk_mul_f32 v[128:129], v[128:129], v[176:177] op_sel_hi:[1,0]
	v_pk_mul_f32 v[122:123], v[122:123], v[176:177] op_sel_hi:[1,0]
	v_pk_mul_f32 v[124:125], v[124:125], v[176:177] op_sel_hi:[1,0]
	v_cvt_pk_bf16_f32 v130, v126, v127
	v_cvt_pk_bf16_f32 v131, v128, v129
	v_cvt_pk_bf16_f32 v132, v122, v123
	v_cvt_pk_bf16_f32 v133, v124, v125
	global_store_dwordx4 v165, v[130:133], s[44:45]
	v_pk_mul_f32 v[110:111], v[110:111], v[178:179] op_sel_hi:[1,0]
	v_pk_mul_f32 v[112:113], v[112:113], v[178:179] op_sel_hi:[1,0]
	v_pk_mul_f32 v[106:107], v[106:107], v[178:179] op_sel_hi:[1,0]
	v_pk_mul_f32 v[108:109], v[108:109], v[178:179] op_sel_hi:[1,0]
	v_cvt_pk_bf16_f32 v134, v110, v111
	v_cvt_pk_bf16_f32 v135, v112, v113
	v_cvt_pk_bf16_f32 v136, v106, v107
	v_cvt_pk_bf16_f32 v137, v108, v109
	global_store_dwordx4 v165, v[134:137], s[44:45] offset:512
	v_pk_mul_f32 v[94:95], v[94:95], v[180:181] op_sel_hi:[1,0]
	v_pk_mul_f32 v[96:97], v[96:97], v[180:181] op_sel_hi:[1,0]
	v_pk_mul_f32 v[90:91], v[90:91], v[180:181] op_sel_hi:[1,0]
	v_pk_mul_f32 v[92:93], v[92:93], v[180:181] op_sel_hi:[1,0]
	v_cvt_pk_bf16_f32 v130, v94, v95
	v_cvt_pk_bf16_f32 v131, v96, v97
	v_cvt_pk_bf16_f32 v132, v90, v91
	v_cvt_pk_bf16_f32 v133, v92, v93
	global_store_dwordx4 v165, v[130:133], s[44:45] offset:1024
	v_pk_mul_f32 v[78:79], v[78:79], v[182:183] op_sel_hi:[1,0]
	v_pk_mul_f32 v[80:81], v[80:81], v[182:183] op_sel_hi:[1,0]
	v_pk_mul_f32 v[74:75], v[74:75], v[182:183] op_sel_hi:[1,0]
	v_pk_mul_f32 v[76:77], v[76:77], v[182:183] op_sel_hi:[1,0]
	v_cvt_pk_bf16_f32 v134, v78, v79
	v_cvt_pk_bf16_f32 v135, v80, v81
	v_cvt_pk_bf16_f32 v136, v74, v75
	v_cvt_pk_bf16_f32 v137, v76, v77
	global_store_dwordx4 v165, v[134:137], s[44:45] offset:1536
	v_add_u32_e32 v166, 0x200000, v165
	v_pk_mul_f32 v[118:119], v[118:119], v[176:177] op_sel_hi:[1,0]
	v_pk_mul_f32 v[120:121], v[120:121], v[176:177] op_sel_hi:[1,0]
	v_pk_mul_f32 v[114:115], v[114:115], v[176:177] op_sel_hi:[1,0]
	v_pk_mul_f32 v[116:117], v[116:117], v[176:177] op_sel_hi:[1,0]
	v_cvt_pk_bf16_f32 v130, v118, v119
	v_cvt_pk_bf16_f32 v131, v120, v121
	v_cvt_pk_bf16_f32 v132, v114, v115
	v_cvt_pk_bf16_f32 v133, v116, v117
	global_store_dwordx4 v166, v[130:133], s[44:45]
	v_pk_mul_f32 v[102:103], v[102:103], v[178:179] op_sel_hi:[1,0]
	v_pk_mul_f32 v[104:105], v[104:105], v[178:179] op_sel_hi:[1,0]
	v_pk_mul_f32 v[98:99], v[98:99], v[178:179] op_sel_hi:[1,0]
	v_pk_mul_f32 v[100:101], v[100:101], v[178:179] op_sel_hi:[1,0]
	v_cvt_pk_bf16_f32 v134, v102, v103
	v_cvt_pk_bf16_f32 v135, v104, v105
	v_cvt_pk_bf16_f32 v136, v98, v99
	v_cvt_pk_bf16_f32 v137, v100, v101
	global_store_dwordx4 v166, v[134:137], s[44:45] offset:512
	v_pk_mul_f32 v[86:87], v[86:87], v[180:181] op_sel_hi:[1,0]
	v_pk_mul_f32 v[88:89], v[88:89], v[180:181] op_sel_hi:[1,0]
	v_pk_mul_f32 v[82:83], v[82:83], v[180:181] op_sel_hi:[1,0]
	v_pk_mul_f32 v[84:85], v[84:85], v[180:181] op_sel_hi:[1,0]
	v_cvt_pk_bf16_f32 v130, v86, v87
	v_cvt_pk_bf16_f32 v131, v88, v89
	v_cvt_pk_bf16_f32 v132, v82, v83
	v_cvt_pk_bf16_f32 v133, v84, v85
	global_store_dwordx4 v166, v[130:133], s[44:45] offset:1024
	v_pk_mul_f32 v[70:71], v[70:71], v[182:183] op_sel_hi:[1,0]
	v_pk_mul_f32 v[72:73], v[72:73], v[182:183] op_sel_hi:[1,0]
	v_pk_mul_f32 v[66:67], v[66:67], v[182:183] op_sel_hi:[1,0]
	v_pk_mul_f32 v[68:69], v[68:69], v[182:183] op_sel_hi:[1,0]
	v_cvt_pk_bf16_f32 v134, v70, v71
	v_cvt_pk_bf16_f32 v135, v72, v73
	v_cvt_pk_bf16_f32 v136, v66, v67
	v_cvt_pk_bf16_f32 v137, v68, v69
	global_store_dwordx4 v166, v[134:137], s[44:45] offset:1536
	v_add_u32_e32 v164, 0x1000, v165
	v_pk_mul_f32 v[62:63], v[62:63], v[184:185] op_sel_hi:[1,0]
	v_pk_mul_f32 v[64:65], v[64:65], v[184:185] op_sel_hi:[1,0]
	v_pk_mul_f32 v[58:59], v[58:59], v[184:185] op_sel_hi:[1,0]
	v_pk_mul_f32 v[60:61], v[60:61], v[184:185] op_sel_hi:[1,0]
	v_cvt_pk_bf16_f32 v130, v62, v63
	v_cvt_pk_bf16_f32 v131, v64, v65
	v_cvt_pk_bf16_f32 v132, v58, v59
	v_cvt_pk_bf16_f32 v133, v60, v61
	global_store_dwordx4 v164, v[130:133], s[44:45]
	v_pk_mul_f32 v[46:47], v[46:47], v[186:187] op_sel_hi:[1,0]
	v_pk_mul_f32 v[48:49], v[48:49], v[186:187] op_sel_hi:[1,0]
	v_pk_mul_f32 v[42:43], v[42:43], v[186:187] op_sel_hi:[1,0]
	v_pk_mul_f32 v[44:45], v[44:45], v[186:187] op_sel_hi:[1,0]
	v_cvt_pk_bf16_f32 v134, v46, v47
	v_cvt_pk_bf16_f32 v135, v48, v49
	v_cvt_pk_bf16_f32 v136, v42, v43
	v_cvt_pk_bf16_f32 v137, v44, v45
	global_store_dwordx4 v164, v[134:137], s[44:45] offset:512
	v_pk_mul_f32 v[30:31], v[30:31], v[188:189] op_sel_hi:[1,0]
	v_pk_mul_f32 v[32:33], v[32:33], v[188:189] op_sel_hi:[1,0]
	v_pk_mul_f32 v[26:27], v[26:27], v[188:189] op_sel_hi:[1,0]
	v_pk_mul_f32 v[28:29], v[28:29], v[188:189] op_sel_hi:[1,0]
	v_cvt_pk_bf16_f32 v130, v30, v31
	v_cvt_pk_bf16_f32 v131, v32, v33
	v_cvt_pk_bf16_f32 v132, v26, v27
	v_cvt_pk_bf16_f32 v133, v28, v29
	global_store_dwordx4 v164, v[130:133], s[44:45] offset:1024
	v_pk_mul_f32 v[14:15], v[14:15], v[190:191] op_sel_hi:[1,0]
	v_pk_mul_f32 v[16:17], v[16:17], v[190:191] op_sel_hi:[1,0]
	v_pk_mul_f32 v[10:11], v[10:11], v[190:191] op_sel_hi:[1,0]
	v_pk_mul_f32 v[12:13], v[12:13], v[190:191] op_sel_hi:[1,0]
	v_cvt_pk_bf16_f32 v134, v14, v15
	v_cvt_pk_bf16_f32 v135, v16, v17
	v_cvt_pk_bf16_f32 v136, v10, v11
	v_cvt_pk_bf16_f32 v137, v12, v13
	global_store_dwordx4 v164, v[134:137], s[44:45] offset:1536
	v_add_u32_e32 v166, 0x201000, v165
	v_pk_mul_f32 v[54:55], v[54:55], v[184:185] op_sel_hi:[1,0]
	v_pk_mul_f32 v[56:57], v[56:57], v[184:185] op_sel_hi:[1,0]
	v_pk_mul_f32 v[50:51], v[50:51], v[184:185] op_sel_hi:[1,0]
	v_pk_mul_f32 v[52:53], v[52:53], v[184:185] op_sel_hi:[1,0]
	v_cvt_pk_bf16_f32 v130, v54, v55
	v_cvt_pk_bf16_f32 v131, v56, v57
	v_cvt_pk_bf16_f32 v132, v50, v51
	v_cvt_pk_bf16_f32 v133, v52, v53
	global_store_dwordx4 v166, v[130:133], s[44:45]
	v_pk_mul_f32 v[38:39], v[38:39], v[186:187] op_sel_hi:[1,0]
	v_pk_mul_f32 v[40:41], v[40:41], v[186:187] op_sel_hi:[1,0]
	v_pk_mul_f32 v[34:35], v[34:35], v[186:187] op_sel_hi:[1,0]
	v_pk_mul_f32 v[36:37], v[36:37], v[186:187] op_sel_hi:[1,0]
	v_cvt_pk_bf16_f32 v134, v38, v39
	v_cvt_pk_bf16_f32 v135, v40, v41
	v_cvt_pk_bf16_f32 v136, v34, v35
	v_cvt_pk_bf16_f32 v137, v36, v37
	global_store_dwordx4 v166, v[134:137], s[44:45] offset:512
	v_pk_mul_f32 v[22:23], v[22:23], v[188:189] op_sel_hi:[1,0]
	v_pk_mul_f32 v[24:25], v[24:25], v[188:189] op_sel_hi:[1,0]
	v_pk_mul_f32 v[18:19], v[18:19], v[188:189] op_sel_hi:[1,0]
	v_pk_mul_f32 v[20:21], v[20:21], v[188:189] op_sel_hi:[1,0]
	v_cvt_pk_bf16_f32 v130, v22, v23
	v_cvt_pk_bf16_f32 v131, v24, v25
	v_cvt_pk_bf16_f32 v132, v18, v19
	v_cvt_pk_bf16_f32 v133, v20, v21
	global_store_dwordx4 v166, v[130:133], s[44:45] offset:1024
	v_pk_mul_f32 v[6:7], v[6:7], v[190:191] op_sel_hi:[1,0]
	v_pk_mul_f32 v[8:9], v[8:9], v[190:191] op_sel_hi:[1,0]
	v_pk_mul_f32 v[2:3], v[2:3], v[190:191] op_sel_hi:[1,0]
	v_pk_mul_f32 v[4:5], v[4:5], v[190:191] op_sel_hi:[1,0]
	v_cvt_pk_bf16_f32 v134, v6, v7
	v_cvt_pk_bf16_f32 v135, v8, v9
	v_cvt_pk_bf16_f32 v136, v2, v3
	v_cvt_pk_bf16_f32 v137, v4, v5
	global_store_dwordx4 v166, v[134:137], s[44:45] offset:1536
	s_branch .Lfe_done
